# instruction selection: the 64 packed f32 multiplies of each SwiGLU GEMM epilogue split into scalar v_mul pairs (both up-projection GEMMs)
# speedup vs baseline: 1.0092x; 1.0092x over previous
; __device__ __forceinline__ unsigned pk2(float lo, float hi) { f32x2_t v = {lo, hi}; bf16x2_t b = __builtin_convertvector(v, bf16x2_t); return __builtin_bit_cast(unsigned, b); }
; #define SWG(a, b) ((a) * (b) * __builtin_amdgcn_rcpf(1.f + __builtin_amdgcn_exp2f(-(a))))
;     __device__ __forceinline__ void operator()(const f32x4 (&acc)[2][2][4][2], const pg8::Unit& u, int wr, int wc, int fr, int fq) const {
;         const int row0 = u.pm * 256 + wr * 64 + fr, col = u.pn * 128 + wc * 32 + 8 * fq;
; #pragma unroll
;         for (int ai = 0; ai < 2; ++ai)
; #pragma unroll
;             for (int m = 0; m < 4; ++m) {
;                 const f32x4 a0 = acc[ai][0][m][0], a1 = acc[ai][0][m][1], b0 = acc[ai][1][m][0], b1 = acc[ai][1][m][1];
;                 u32x4 w;
;     ...
;                 w.x = pk2(SWG(a0[0], b0[0]), SWG(a0[1], b0[1])); w.y = pk2(SWG(a0[2], b0[2]), SWG(a0[3], b0[3]));
;                 w.z = pk2(SWG(a1[0], b1[0]), SWG(a1[1], b1[1])); w.w = pk2(SWG(a1[2], b1[2]), SWG(a1[3], b1[3]));
;     ...
;                 *(u32x4*)(H + (size_t)(row0 + ai * 128 + m * 16) * DFF + col) = w;
;             }
.LBB0_406:
	v_exp_f32_e64 v148, -v122
	v_exp_f32_e64 v149, -v123
	v_mul_f32_e32 v122, v122, v126
	v_mul_f32_e32 v123, v123, v127
	v_mul_f32_e32 v128, v124, v128
	v_mul_f32_e32 v129, v125, v129
	v_add_f32_e32 v148, 1.0, v148
	v_add_f32_e32 v149, 1.0, v149
	v_rcp_f32_e32 v148, v148
	v_rcp_f32_e32 v149, v149
	v_mul_f32_e32 v120, v116, v120
	v_mul_f32_e32 v121, v117, v121
	v_lshl_or_b32 v146, s13, 7, v143
	v_lshl_add_u32 v145, s22, 8, v0
	v_mul_f32_e32 v122, v148, v122
	v_mul_f32_e32 v123, v149, v123
	v_ashrrev_i32_e32 v147, 31, v146
	v_cvt_pk_bf16_f32 v122, v122, v123
	v_exp_f32_e64 v123, -v124
	v_mul_f32_e32 v112, v108, v112
	v_mul_f32_e32 v113, v109, v113
	v_mul_f32_e32 v104, v100, v104
	v_mul_f32_e32 v105, v101, v105
	v_mul_f32_e32 v96, v92, v96
	v_mul_f32_e32 v97, v93, v97
	v_add_f32_e32 v123, 1.0, v123
	v_rcp_f32_e32 v124, v123
	v_exp_f32_e64 v123, -v125
	v_mul_f32_e32 v88, v84, v88
	v_mul_f32_e32 v89, v85, v89
	v_mul_f32_e32 v80, v76, v80
	v_mul_f32_e32 v81, v77, v81
	v_mul_f32_e32 v72, v68, v72
	v_mul_f32_e32 v73, v69, v73
	v_add_f32_e32 v123, 1.0, v123
	v_rcp_f32_e32 v125, v123
	v_mul_f32_e32 v64, v60, v64
	v_mul_f32_e32 v65, v61, v65
	v_mul_f32_e32 v56, v52, v56
	v_mul_f32_e32 v57, v53, v57
	v_mul_f32_e32 v48, v44, v48
	v_mul_f32_e32 v49, v45, v49
	v_mul_f32_e32 v124, v124, v128
	v_mul_f32_e32 v125, v125, v129
	v_mul_f32_e32 v40, v36, v40
	v_mul_f32_e32 v41, v37, v41
	v_cvt_pk_bf16_f32 v123, v124, v125
	v_exp_f32_e64 v124, -v114
	v_exp_f32_e64 v125, -v115
	v_mul_f32_e32 v114, v114, v118
	v_mul_f32_e32 v115, v115, v119
	v_mul_f32_e32 v32, v28, v32
	v_mul_f32_e32 v33, v29, v33
	v_add_f32_e32 v124, 1.0, v124
	v_add_f32_e32 v125, 1.0, v125
	v_rcp_f32_e32 v124, v124
	v_rcp_f32_e32 v125, v125
	v_mul_f32_e32 v24, v20, v24
	v_mul_f32_e32 v25, v21, v25
	v_mul_f32_e32 v16, v12, v16
	v_mul_f32_e32 v17, v13, v17
	v_mul_f32_e32 v8, v4, v8
	v_mul_f32_e32 v9, v5, v9
	v_mul_f32_e32 v114, v124, v114
	v_mul_f32_e32 v115, v125, v115
	s_andn2_b64 vcc, exec, s[36:37]
	v_cvt_pk_bf16_f32 v124, v114, v115
	v_exp_f32_e64 v114, -v116
	v_exp_f32_e64 v115, -v117
	v_lshlrev_b64 v[116:117], 1, v[146:147]
	v_add_f32_e32 v114, 1.0, v114
	v_add_f32_e32 v115, 1.0, v115
	v_rcp_f32_e32 v114, v114
	v_rcp_f32_e32 v115, v115
	s_nop 0
	v_mul_f32_e32 v114, v114, v120
	v_mul_f32_e32 v115, v115, v121
	s_nop 0
	v_cvt_pk_bf16_f32 v125, v114, v115
	v_mov_b64_e32 v[114:115], s[30:31]
	v_mad_i64_i32 v[118:119], s[4:5], v145, s16, v[114:115]
	v_lshl_add_u64 v[118:119], v[118:119], 0, v[116:117]
	global_store_dwordx4 v[118:119], v[122:125], off
	v_exp_f32_e64 v118, -v106
	v_exp_f32_e64 v119, -v107
	v_mul_f32_e32 v106, v106, v110
	v_mul_f32_e32 v107, v107, v111
	v_add_f32_e32 v118, 1.0, v118
	v_add_f32_e32 v119, 1.0, v119
	v_rcp_f32_e32 v118, v118
	v_rcp_f32_e32 v119, v119
	s_nop 0
	v_mul_f32_e32 v106, v118, v106
	v_mul_f32_e32 v107, v119, v107
	s_nop 0
	v_cvt_pk_bf16_f32 v106, v106, v107
	v_exp_f32_e64 v107, -v108
	s_nop 0
	v_add_f32_e32 v107, 1.0, v107
	v_rcp_f32_e32 v108, v107
	v_exp_f32_e64 v107, -v109
	s_nop 0
	v_add_f32_e32 v107, 1.0, v107
	v_rcp_f32_e32 v109, v107
	s_nop 0
	v_mul_f32_e32 v108, v108, v112
	v_mul_f32_e32 v109, v109, v113
	s_nop 0
	v_cvt_pk_bf16_f32 v107, v108, v109
	v_exp_f32_e64 v108, -v98
	v_exp_f32_e64 v109, -v99
	v_mul_f32_e32 v98, v98, v102
	v_mul_f32_e32 v99, v99, v103
	v_add_f32_e32 v108, 1.0, v108
	v_add_f32_e32 v109, 1.0, v109
	v_rcp_f32_e32 v108, v108
	v_rcp_f32_e32 v109, v109
	s_nop 0
	v_mul_f32_e32 v98, v108, v98
	v_mul_f32_e32 v99, v109, v99
	s_nop 0
	v_cvt_pk_bf16_f32 v108, v98, v99
	v_exp_f32_e64 v98, -v100
	v_exp_f32_e64 v99, -v101
	v_add_f32_e32 v98, 1.0, v98
	v_add_f32_e32 v99, 1.0, v99
	v_rcp_f32_e32 v98, v98
	v_rcp_f32_e32 v99, v99
	s_nop 0
	v_mul_f32_e32 v98, v98, v104
	v_mul_f32_e32 v99, v99, v105
	s_nop 0
	v_cvt_pk_bf16_f32 v109, v98, v99
	v_or_b32_e32 v98, 16, v145
	v_mad_i64_i32 v[98:99], s[4:5], v98, s16, v[114:115]
	v_lshl_add_u64 v[98:99], v[98:99], 0, v[116:117]
	global_store_dwordx4 v[98:99], v[106:109], off
	v_exp_f32_e64 v98, -v90
	v_exp_f32_e64 v99, -v91
	v_mul_f32_e32 v90, v90, v94
	v_mul_f32_e32 v91, v91, v95
	v_add_f32_e32 v98, 1.0, v98
	v_add_f32_e32 v99, 1.0, v99
	v_rcp_f32_e32 v98, v98
	v_rcp_f32_e32 v99, v99
	s_nop 0
	v_mul_f32_e32 v90, v98, v90
	v_mul_f32_e32 v91, v99, v91
	s_nop 0
	v_cvt_pk_bf16_f32 v90, v90, v91
	v_exp_f32_e64 v91, -v92
	s_nop 0
	v_add_f32_e32 v91, 1.0, v91
	v_rcp_f32_e32 v92, v91
	v_exp_f32_e64 v91, -v93
	s_nop 0
	v_add_f32_e32 v91, 1.0, v91
	v_rcp_f32_e32 v93, v91
	s_nop 0
	v_mul_f32_e32 v92, v92, v96
	v_mul_f32_e32 v93, v93, v97
	s_nop 0
	v_cvt_pk_bf16_f32 v91, v92, v93
	v_exp_f32_e64 v92, -v82
	v_exp_f32_e64 v93, -v83
	v_mul_f32_e32 v82, v82, v86
	v_mul_f32_e32 v83, v83, v87
	v_add_f32_e32 v92, 1.0, v92
	v_add_f32_e32 v93, 1.0, v93
	v_rcp_f32_e32 v92, v92
	v_rcp_f32_e32 v93, v93
	s_nop 0
	v_mul_f32_e32 v82, v92, v82
	v_mul_f32_e32 v83, v93, v83
	s_nop 0
	v_cvt_pk_bf16_f32 v92, v82, v83
	v_exp_f32_e64 v82, -v84
	v_exp_f32_e64 v83, -v85
	v_add_f32_e32 v82, 1.0, v82
	v_add_f32_e32 v83, 1.0, v83
	v_rcp_f32_e32 v82, v82
	v_rcp_f32_e32 v83, v83
	s_nop 0
	v_mul_f32_e32 v82, v82, v88
	v_mul_f32_e32 v83, v83, v89
	s_nop 0
	v_cvt_pk_bf16_f32 v93, v82, v83
	v_or_b32_e32 v82, 32, v145
	v_mad_i64_i32 v[82:83], s[4:5], v82, s16, v[114:115]
	v_lshl_add_u64 v[82:83], v[82:83], 0, v[116:117]
	global_store_dwordx4 v[82:83], v[90:93], off
	v_exp_f32_e64 v82, -v74
	v_exp_f32_e64 v83, -v75
	v_mul_f32_e32 v74, v74, v78
	v_mul_f32_e32 v75, v75, v79
	v_add_f32_e32 v82, 1.0, v82
	v_add_f32_e32 v83, 1.0, v83
	v_rcp_f32_e32 v82, v82
	v_rcp_f32_e32 v83, v83
	s_nop 0
	v_mul_f32_e32 v74, v82, v74
	v_mul_f32_e32 v75, v83, v75
; __device__ __forceinline__ unsigned pk2(float lo, float hi) { f32x2_t v = {lo, hi}; bf16x2_t b = __builtin_convertvector(v, bf16x2_t); return __builtin_bit_cast(unsigned, b); }
; #define SWG(a, b) ((a) * (b) * __builtin_amdgcn_rcpf(1.f + __builtin_amdgcn_exp2f(-(a))))
;     __device__ __forceinline__ void operator()(const f32x4 (&acc)[2][2][4][2], const pg8::Unit& u, int wr, int wc, int fr, int fq) const {
;     ...
; #pragma unroll
;         for (int ai = 0; ai < 2; ++ai)
; #pragma unroll
;             for (int m = 0; m < 4; ++m) {
;                 const f32x4 a0 = acc[ai][0][m][0], a1 = acc[ai][0][m][1], b0 = acc[ai][1][m][0], b1 = acc[ai][1][m][1];
;                 u32x4 w;
;     ...
;                 w.x = pk2(SWG(a0[0], b0[0]), SWG(a0[1], b0[1])); w.y = pk2(SWG(a0[2], b0[2]), SWG(a0[3], b0[3]));
;                 w.z = pk2(SWG(a1[0], b1[0]), SWG(a1[1], b1[1])); w.w = pk2(SWG(a1[2], b1[2]), SWG(a1[3], b1[3]));
;     ...
;                 *(u32x4*)(H + (size_t)(row0 + ai * 128 + m * 16) * DFF + col) = w;
;             }
	s_nop 0
	v_cvt_pk_bf16_f32 v74, v74, v75
	v_exp_f32_e64 v75, -v76
	s_nop 0
	v_add_f32_e32 v75, 1.0, v75
	v_rcp_f32_e32 v76, v75
	v_exp_f32_e64 v75, -v77
	s_nop 0
	v_add_f32_e32 v75, 1.0, v75
	v_rcp_f32_e32 v77, v75
	s_nop 0
	v_mul_f32_e32 v76, v76, v80
	v_mul_f32_e32 v77, v77, v81
	s_nop 0
	v_cvt_pk_bf16_f32 v75, v76, v77
	v_exp_f32_e64 v76, -v66
	v_exp_f32_e64 v77, -v67
	v_mul_f32_e32 v66, v66, v70
	v_mul_f32_e32 v67, v67, v71
	v_add_f32_e32 v76, 1.0, v76
	v_add_f32_e32 v77, 1.0, v77
	v_rcp_f32_e32 v76, v76
	v_rcp_f32_e32 v77, v77
	s_nop 0
	v_mul_f32_e32 v66, v76, v66
	v_mul_f32_e32 v67, v77, v67
	s_nop 0
	v_cvt_pk_bf16_f32 v76, v66, v67
	v_exp_f32_e64 v66, -v68
	v_exp_f32_e64 v67, -v69
	v_add_u32_e32 v68, 0x80, v145
	v_add_f32_e32 v66, 1.0, v66
	v_add_f32_e32 v67, 1.0, v67
	v_rcp_f32_e32 v66, v66
	v_rcp_f32_e32 v67, v67
	s_nop 0
	v_mul_f32_e32 v66, v66, v72
	v_mul_f32_e32 v67, v67, v73
	s_nop 0
	v_cvt_pk_bf16_f32 v77, v66, v67
	v_or_b32_e32 v66, 48, v145
	v_mad_i64_i32 v[66:67], s[4:5], v66, s16, v[114:115]
	v_lshl_add_u64 v[66:67], v[66:67], 0, v[116:117]
	global_store_dwordx4 v[66:67], v[74:77], off
	v_exp_f32_e64 v66, -v58
	v_exp_f32_e64 v67, -v59
	v_mul_f32_e32 v58, v58, v62
	v_mul_f32_e32 v59, v59, v63
	v_add_f32_e32 v66, 1.0, v66
	v_add_f32_e32 v67, 1.0, v67
	v_rcp_f32_e32 v66, v66
	v_rcp_f32_e32 v67, v67
	s_nop 0
	v_mul_f32_e32 v58, v66, v58
	v_mul_f32_e32 v59, v67, v59
	s_nop 0
	v_cvt_pk_bf16_f32 v58, v58, v59
	v_exp_f32_e64 v59, -v60
	s_nop 0
	v_add_f32_e32 v59, 1.0, v59
	v_rcp_f32_e32 v60, v59
	v_exp_f32_e64 v59, -v61
	s_nop 0
	v_add_f32_e32 v59, 1.0, v59
	v_rcp_f32_e32 v61, v59
	s_nop 0
	v_mul_f32_e32 v60, v60, v64
	v_mul_f32_e32 v61, v61, v65
	s_nop 0
	v_cvt_pk_bf16_f32 v59, v60, v61
	v_exp_f32_e64 v60, -v50
	v_exp_f32_e64 v61, -v51
	v_mul_f32_e32 v50, v50, v54
	v_mul_f32_e32 v51, v51, v55
	v_add_f32_e32 v60, 1.0, v60
	v_add_f32_e32 v61, 1.0, v61
	v_rcp_f32_e32 v60, v60
	v_rcp_f32_e32 v61, v61
	s_nop 0
	v_mul_f32_e32 v50, v60, v50
	v_mul_f32_e32 v51, v61, v51
	s_nop 0
	v_cvt_pk_bf16_f32 v60, v50, v51
	v_exp_f32_e64 v50, -v52
	v_exp_f32_e64 v51, -v53
	v_add_f32_e32 v50, 1.0, v50
	v_add_f32_e32 v51, 1.0, v51
	v_rcp_f32_e32 v50, v50
	v_rcp_f32_e32 v51, v51
	s_nop 0
	v_mul_f32_e32 v50, v50, v56
	v_mul_f32_e32 v51, v51, v57
	s_nop 0
	v_cvt_pk_bf16_f32 v61, v50, v51
	v_mad_i64_i32 v[50:51], s[4:5], v68, s16, v[114:115]
	v_lshl_add_u64 v[50:51], v[50:51], 0, v[116:117]
	global_store_dwordx4 v[50:51], v[58:61], off
	v_exp_f32_e64 v50, -v42
	v_exp_f32_e64 v51, -v43
	v_mul_f32_e32 v42, v42, v46
	v_mul_f32_e32 v43, v43, v47
	v_add_f32_e32 v50, 1.0, v50
	v_add_f32_e32 v51, 1.0, v51
	v_rcp_f32_e32 v50, v50
	v_rcp_f32_e32 v51, v51
	s_nop 0
	v_mul_f32_e32 v42, v50, v42
	v_mul_f32_e32 v43, v51, v43
	s_nop 0
	v_cvt_pk_bf16_f32 v42, v42, v43
	v_exp_f32_e64 v43, -v44
	s_nop 0
	v_add_f32_e32 v43, 1.0, v43
	v_rcp_f32_e32 v44, v43
	v_exp_f32_e64 v43, -v45
	s_nop 0
	v_add_f32_e32 v43, 1.0, v43
	v_rcp_f32_e32 v45, v43
	s_nop 0
	v_mul_f32_e32 v44, v44, v48
	v_mul_f32_e32 v45, v45, v49
	s_nop 0
	v_cvt_pk_bf16_f32 v43, v44, v45
	v_exp_f32_e64 v44, -v34
	v_exp_f32_e64 v45, -v35
	v_mul_f32_e32 v34, v34, v38
	v_mul_f32_e32 v35, v35, v39
	v_add_f32_e32 v44, 1.0, v44
	v_add_f32_e32 v45, 1.0, v45
	v_rcp_f32_e32 v44, v44
	v_rcp_f32_e32 v45, v45
	s_nop 0
	v_mul_f32_e32 v34, v44, v34
	v_mul_f32_e32 v35, v45, v35
	s_nop 0
	v_cvt_pk_bf16_f32 v44, v34, v35
	v_exp_f32_e64 v34, -v36
	v_exp_f32_e64 v35, -v37
	v_add_f32_e32 v34, 1.0, v34
	v_add_f32_e32 v35, 1.0, v35
	v_rcp_f32_e32 v34, v34
	v_rcp_f32_e32 v35, v35
	s_nop 0
	v_mul_f32_e32 v34, v34, v40
	v_mul_f32_e32 v35, v35, v41
	s_nop 0
	v_cvt_pk_bf16_f32 v45, v34, v35
	v_add_u32_e32 v34, 0x90, v145
	v_mad_i64_i32 v[34:35], s[4:5], v34, s16, v[114:115]
	v_lshl_add_u64 v[34:35], v[34:35], 0, v[116:117]
	global_store_dwordx4 v[34:35], v[42:45], off
	v_exp_f32_e64 v34, -v26
	v_exp_f32_e64 v35, -v27
	v_mul_f32_e32 v26, v26, v30
	v_mul_f32_e32 v27, v27, v31
	v_add_f32_e32 v34, 1.0, v34
	v_add_f32_e32 v35, 1.0, v35
	v_rcp_f32_e32 v34, v34
	v_rcp_f32_e32 v35, v35
	s_nop 0
	v_mul_f32_e32 v26, v34, v26
	v_mul_f32_e32 v27, v35, v27
	s_nop 0
	v_cvt_pk_bf16_f32 v26, v26, v27
	v_exp_f32_e64 v27, -v28
	s_nop 0
	v_add_f32_e32 v27, 1.0, v27
	v_rcp_f32_e32 v28, v27
	v_exp_f32_e64 v27, -v29
	s_nop 0
	v_add_f32_e32 v27, 1.0, v27
	v_rcp_f32_e32 v29, v27
	s_nop 0
	v_mul_f32_e32 v28, v28, v32
	v_mul_f32_e32 v29, v29, v33
	s_nop 0
	v_cvt_pk_bf16_f32 v27, v28, v29
	v_exp_f32_e64 v28, -v18
	v_exp_f32_e64 v29, -v19
	v_mul_f32_e32 v18, v18, v22
	v_mul_f32_e32 v19, v19, v23
	v_add_f32_e32 v28, 1.0, v28
	v_add_f32_e32 v29, 1.0, v29
	v_rcp_f32_e32 v28, v28
	v_rcp_f32_e32 v29, v29
	s_nop 0
	v_mul_f32_e32 v18, v28, v18
	v_mul_f32_e32 v19, v29, v19
	s_nop 0
	v_cvt_pk_bf16_f32 v28, v18, v19
	v_exp_f32_e64 v18, -v20
	v_exp_f32_e64 v19, -v21
	v_add_f32_e32 v18, 1.0, v18
	v_add_f32_e32 v19, 1.0, v19
	v_rcp_f32_e32 v18, v18
	v_rcp_f32_e32 v19, v19
	s_nop 0
	v_mul_f32_e32 v18, v18, v24
	v_mul_f32_e32 v19, v19, v25
	s_nop 0
	v_cvt_pk_bf16_f32 v29, v18, v19
	v_add_u32_e32 v18, 0xa0, v145
	v_mad_i64_i32 v[18:19], s[4:5], v18, s16, v[114:115]
	v_lshl_add_u64 v[18:19], v[18:19], 0, v[116:117]
	global_store_dwordx4 v[18:19], v[26:29], off
	v_exp_f32_e64 v18, -v10
	v_exp_f32_e64 v19, -v11
	v_mul_f32_e32 v10, v10, v14
	v_mul_f32_e32 v11, v11, v15
	v_add_f32_e32 v18, 1.0, v18
	v_add_f32_e32 v19, 1.0, v19
	v_rcp_f32_e32 v18, v18
	v_rcp_f32_e32 v19, v19
	s_nop 0
	v_mul_f32_e32 v10, v18, v10
	v_mul_f32_e32 v11, v19, v11
	s_nop 0
	v_cvt_pk_bf16_f32 v10, v10, v11
	v_exp_f32_e64 v11, -v12
	s_nop 0
	v_add_f32_e32 v11, 1.0, v11
	v_rcp_f32_e32 v12, v11
	v_exp_f32_e64 v11, -v13
	s_nop 0
	v_add_f32_e32 v11, 1.0, v11
	v_rcp_f32_e32 v13, v11
	s_nop 0
	v_mul_f32_e32 v12, v12, v16
	v_mul_f32_e32 v13, v13, v17
	s_nop 0
	v_cvt_pk_bf16_f32 v11, v12, v13
	v_exp_f32_e64 v12, -v2
	v_exp_f32_e64 v13, -v3
	v_mul_f32_e32 v2, v2, v6
	v_mul_f32_e32 v3, v3, v7
	v_add_f32_e32 v12, 1.0, v12
	v_add_f32_e32 v13, 1.0, v13
	v_rcp_f32_e32 v12, v12
	v_rcp_f32_e32 v13, v13
	s_nop 0
	v_mul_f32_e32 v2, v12, v2
	v_mul_f32_e32 v3, v13, v3
	s_nop 0
	v_cvt_pk_bf16_f32 v12, v2, v3
	v_exp_f32_e64 v2, -v4
	v_exp_f32_e64 v3, -v5
	v_add_f32_e32 v2, 1.0, v2
	v_add_f32_e32 v3, 1.0, v3
	v_rcp_f32_e32 v2, v2
	v_rcp_f32_e32 v3, v3
	s_nop 0
	v_mul_f32_e32 v2, v2, v8
	v_mul_f32_e32 v3, v3, v9
	s_nop 0
	v_cvt_pk_bf16_f32 v13, v2, v3
	v_add_u32_e32 v2, 0xb0, v145
	v_mad_i64_i32 v[2:3], s[4:5], v2, s16, v[114:115]
	v_lshl_add_u64 v[2:3], v[2:3], 0, v[116:117]
	s_mov_b64 s[4:5], -1
	global_store_dwordx4 v[2:3], v[10:13], off
	s_cbranch_vccnz .LBB0_399
	s_andn2_b64 vcc, exec, s[38:39]
	s_cbranch_vccnz .LBB0_398
	s_barrier
	s_branch .LBB0_398

; __device__ __forceinline__ unsigned pk2(float lo, float hi) { f32x2_t v = {lo, hi}; bf16x2_t b = __builtin_convertvector(v, bf16x2_t); return __builtin_bit_cast(unsigned, b); }
; #define SWG(a, b) ((a) * (b) * __builtin_amdgcn_rcpf(1.f + __builtin_amdgcn_exp2f(-(a))))
;     __device__ __forceinline__ void operator()(const f32x4 (&acc)[2][2][4][2], const pg8::Unit& u, int wr, int wc, int fr, int fq) const {
;         const int row0 = u.pm * 256 + wr * 64 + fr, col = u.pn * 128 + wc * 32 + 8 * fq;
; #pragma unroll
;         for (int ai = 0; ai < 2; ++ai)
; #pragma unroll
;             for (int m = 0; m < 4; ++m) {
;                 const f32x4 a0 = acc[ai][0][m][0], a1 = acc[ai][0][m][1], b0 = acc[ai][1][m][0], b1 = acc[ai][1][m][1];
;                 u32x4 w;
;     ...
;                 w.x = pk2(SWG(a0[0], b0[0]), SWG(a0[1], b0[1])); w.y = pk2(SWG(a0[2], b0[2]), SWG(a0[3], b0[3]));
;                 w.z = pk2(SWG(a1[0], b1[0]), SWG(a1[1], b1[1])); w.w = pk2(SWG(a1[2], b1[2]), SWG(a1[3], b1[3]));
;     ...
;                 *(u32x4*)(H + (size_t)(row0 + ai * 128 + m * 16) * DFF + col) = w;
;             }
.LBB0_1667:
	v_exp_f32_e64 v148, -v122
	v_exp_f32_e64 v149, -v123
	v_mul_f32_e32 v122, v122, v126
	v_mul_f32_e32 v123, v123, v127
	v_mul_f32_e32 v128, v124, v128
	v_mul_f32_e32 v129, v125, v129
	v_add_f32_e32 v148, 1.0, v148
	v_add_f32_e32 v149, 1.0, v149
	v_rcp_f32_e32 v148, v148
	v_rcp_f32_e32 v149, v149
	v_mul_f32_e32 v120, v116, v120
	v_mul_f32_e32 v121, v117, v121
	v_lshl_or_b32 v146, s13, 7, v143
	v_lshl_add_u32 v145, s48, 8, v0
	v_mul_f32_e32 v122, v148, v122
	v_mul_f32_e32 v123, v149, v123
	v_ashrrev_i32_e32 v147, 31, v146
	v_cvt_pk_bf16_f32 v122, v122, v123
	v_exp_f32_e64 v123, -v124
	v_mul_f32_e32 v112, v108, v112
	v_mul_f32_e32 v113, v109, v113
	v_mul_f32_e32 v104, v100, v104
	v_mul_f32_e32 v105, v101, v105
	v_mul_f32_e32 v96, v92, v96
	v_mul_f32_e32 v97, v93, v97
	v_add_f32_e32 v123, 1.0, v123
	v_rcp_f32_e32 v124, v123
	v_exp_f32_e64 v123, -v125
	v_mul_f32_e32 v88, v84, v88
	v_mul_f32_e32 v89, v85, v89
	v_mul_f32_e32 v80, v76, v80
	v_mul_f32_e32 v81, v77, v81
	v_mul_f32_e32 v72, v68, v72
	v_mul_f32_e32 v73, v69, v73
	v_add_f32_e32 v123, 1.0, v123
	v_rcp_f32_e32 v125, v123
	v_mul_f32_e32 v64, v60, v64
	v_mul_f32_e32 v65, v61, v65
	v_mul_f32_e32 v56, v52, v56
	v_mul_f32_e32 v57, v53, v57
	v_mul_f32_e32 v48, v44, v48
	v_mul_f32_e32 v49, v45, v49
	v_mul_f32_e32 v124, v124, v128
	v_mul_f32_e32 v125, v125, v129
	v_mul_f32_e32 v40, v36, v40
	v_mul_f32_e32 v41, v37, v41
	v_cvt_pk_bf16_f32 v123, v124, v125
	v_exp_f32_e64 v124, -v114
	v_exp_f32_e64 v125, -v115
	v_mul_f32_e32 v114, v114, v118
	v_mul_f32_e32 v115, v115, v119
	v_mul_f32_e32 v32, v28, v32
	v_mul_f32_e32 v33, v29, v33
	v_add_f32_e32 v124, 1.0, v124
	v_add_f32_e32 v125, 1.0, v125
	v_rcp_f32_e32 v124, v124
	v_rcp_f32_e32 v125, v125
	v_mul_f32_e32 v24, v20, v24
	v_mul_f32_e32 v25, v21, v25
	v_mul_f32_e32 v16, v12, v16
	v_mul_f32_e32 v17, v13, v17
	v_mul_f32_e32 v8, v4, v8
	v_mul_f32_e32 v9, v5, v9
	v_mul_f32_e32 v114, v124, v114
	v_mul_f32_e32 v115, v125, v115
	s_andn2_b64 vcc, exec, s[38:39]
	v_cvt_pk_bf16_f32 v124, v114, v115
	v_exp_f32_e64 v114, -v116
	v_exp_f32_e64 v115, -v117
	v_lshlrev_b64 v[116:117], 1, v[146:147]
	s_mov_b32 s33, 0x10000
	v_add_f32_e32 v114, 1.0, v114
	v_add_f32_e32 v115, 1.0, v115
	v_rcp_f32_e32 v114, v114
	v_rcp_f32_e32 v115, v115
	s_nop 0
	v_mul_f32_e32 v114, v114, v120
	v_mul_f32_e32 v115, v115, v121
	s_nop 0
	v_cvt_pk_bf16_f32 v125, v114, v115
	v_mov_b64_e32 v[114:115], s[30:31]
	v_mad_i64_i32 v[118:119], s[4:5], v145, s16, v[114:115]
	v_lshl_add_u64 v[118:119], v[118:119], 0, v[116:117]
	global_store_dwordx4 v[118:119], v[122:125], off
	v_exp_f32_e64 v118, -v106
	v_exp_f32_e64 v119, -v107
	v_mul_f32_e32 v106, v106, v110
	v_mul_f32_e32 v107, v107, v111
	v_add_f32_e32 v118, 1.0, v118
	v_add_f32_e32 v119, 1.0, v119
	v_rcp_f32_e32 v118, v118
	v_rcp_f32_e32 v119, v119
	s_nop 0
	v_mul_f32_e32 v106, v118, v106
	v_mul_f32_e32 v107, v119, v107
	s_nop 0
	v_cvt_pk_bf16_f32 v106, v106, v107
	v_exp_f32_e64 v107, -v108
	s_nop 0
	v_add_f32_e32 v107, 1.0, v107
	v_rcp_f32_e32 v108, v107
	v_exp_f32_e64 v107, -v109
	s_nop 0
	v_add_f32_e32 v107, 1.0, v107
	v_rcp_f32_e32 v109, v107
	s_nop 0
	v_mul_f32_e32 v108, v108, v112
	v_mul_f32_e32 v109, v109, v113
	s_nop 0
	v_cvt_pk_bf16_f32 v107, v108, v109
	v_exp_f32_e64 v108, -v98
	v_exp_f32_e64 v109, -v99
	v_mul_f32_e32 v98, v98, v102
	v_mul_f32_e32 v99, v99, v103
	v_add_f32_e32 v108, 1.0, v108
	v_add_f32_e32 v109, 1.0, v109
	v_rcp_f32_e32 v108, v108
	v_rcp_f32_e32 v109, v109
	s_nop 0
	v_mul_f32_e32 v98, v108, v98
	v_mul_f32_e32 v99, v109, v99
	s_nop 0
	v_cvt_pk_bf16_f32 v108, v98, v99
	v_exp_f32_e64 v98, -v100
	v_exp_f32_e64 v99, -v101
	v_add_f32_e32 v98, 1.0, v98
	v_add_f32_e32 v99, 1.0, v99
	v_rcp_f32_e32 v98, v98
	v_rcp_f32_e32 v99, v99
	s_nop 0
	v_mul_f32_e32 v98, v98, v104
	v_mul_f32_e32 v99, v99, v105
	s_nop 0
	v_cvt_pk_bf16_f32 v109, v98, v99
	v_or_b32_e32 v98, 16, v145
	v_mad_i64_i32 v[98:99], s[4:5], v98, s16, v[114:115]
	v_lshl_add_u64 v[98:99], v[98:99], 0, v[116:117]
	global_store_dwordx4 v[98:99], v[106:109], off
	v_exp_f32_e64 v98, -v90
	v_exp_f32_e64 v99, -v91
	v_mul_f32_e32 v90, v90, v94
	v_mul_f32_e32 v91, v91, v95
	v_add_f32_e32 v98, 1.0, v98
	v_add_f32_e32 v99, 1.0, v99
	v_rcp_f32_e32 v98, v98
	v_rcp_f32_e32 v99, v99
	s_nop 0
	v_mul_f32_e32 v90, v98, v90
	v_mul_f32_e32 v91, v99, v91
	s_nop 0
	v_cvt_pk_bf16_f32 v90, v90, v91
	v_exp_f32_e64 v91, -v92
	s_nop 0
	v_add_f32_e32 v91, 1.0, v91
	v_rcp_f32_e32 v92, v91
	v_exp_f32_e64 v91, -v93
	s_nop 0
	v_add_f32_e32 v91, 1.0, v91
	v_rcp_f32_e32 v93, v91
	s_nop 0
	v_mul_f32_e32 v92, v92, v96
	v_mul_f32_e32 v93, v93, v97
	s_nop 0
	v_cvt_pk_bf16_f32 v91, v92, v93
	v_exp_f32_e64 v92, -v82
	v_exp_f32_e64 v93, -v83
	v_mul_f32_e32 v82, v82, v86
	v_mul_f32_e32 v83, v83, v87
	v_add_f32_e32 v92, 1.0, v92
	v_add_f32_e32 v93, 1.0, v93
	v_rcp_f32_e32 v92, v92
	v_rcp_f32_e32 v93, v93
	s_nop 0
	v_mul_f32_e32 v82, v92, v82
	v_mul_f32_e32 v83, v93, v83
	s_nop 0
	v_cvt_pk_bf16_f32 v92, v82, v83
	v_exp_f32_e64 v82, -v84
	v_exp_f32_e64 v83, -v85
	v_add_f32_e32 v82, 1.0, v82
	v_add_f32_e32 v83, 1.0, v83
	v_rcp_f32_e32 v82, v82
	v_rcp_f32_e32 v83, v83
	s_nop 0
	v_mul_f32_e32 v82, v82, v88
	v_mul_f32_e32 v83, v83, v89
	s_nop 0
	v_cvt_pk_bf16_f32 v93, v82, v83
	v_or_b32_e32 v82, 32, v145
	v_mad_i64_i32 v[82:83], s[4:5], v82, s16, v[114:115]
	v_lshl_add_u64 v[82:83], v[82:83], 0, v[116:117]
	global_store_dwordx4 v[82:83], v[90:93], off
	v_exp_f32_e64 v82, -v74
	v_exp_f32_e64 v83, -v75
	v_mul_f32_e32 v74, v74, v78
	v_mul_f32_e32 v75, v75, v79
	v_add_f32_e32 v82, 1.0, v82
	v_add_f32_e32 v83, 1.0, v83
	v_rcp_f32_e32 v82, v82
	v_rcp_f32_e32 v83, v83
	s_nop 0
	v_mul_f32_e32 v74, v82, v74
; __device__ __forceinline__ unsigned pk2(float lo, float hi) { f32x2_t v = {lo, hi}; bf16x2_t b = __builtin_convertvector(v, bf16x2_t); return __builtin_bit_cast(unsigned, b); }
; #define SWG(a, b) ((a) * (b) * __builtin_amdgcn_rcpf(1.f + __builtin_amdgcn_exp2f(-(a))))
;     __device__ __forceinline__ void operator()(const f32x4 (&acc)[2][2][4][2], const pg8::Unit& u, int wr, int wc, int fr, int fq) const {
;     ...
; #pragma unroll
;         for (int ai = 0; ai < 2; ++ai)
; #pragma unroll
;             for (int m = 0; m < 4; ++m) {
;                 const f32x4 a0 = acc[ai][0][m][0], a1 = acc[ai][0][m][1], b0 = acc[ai][1][m][0], b1 = acc[ai][1][m][1];
;                 u32x4 w;
;     ...
;                 w.x = pk2(SWG(a0[0], b0[0]), SWG(a0[1], b0[1])); w.y = pk2(SWG(a0[2], b0[2]), SWG(a0[3], b0[3]));
;                 w.z = pk2(SWG(a1[0], b1[0]), SWG(a1[1], b1[1])); w.w = pk2(SWG(a1[2], b1[2]), SWG(a1[3], b1[3]));
;     ...
;                 *(u32x4*)(H + (size_t)(row0 + ai * 128 + m * 16) * DFF + col) = w;
;             }
	v_mul_f32_e32 v75, v83, v75
	s_nop 0
	v_cvt_pk_bf16_f32 v74, v74, v75
	v_exp_f32_e64 v75, -v76
	s_nop 0
	v_add_f32_e32 v75, 1.0, v75
	v_rcp_f32_e32 v76, v75
	v_exp_f32_e64 v75, -v77
	s_nop 0
	v_add_f32_e32 v75, 1.0, v75
	v_rcp_f32_e32 v77, v75
	s_nop 0
	v_mul_f32_e32 v76, v76, v80
	v_mul_f32_e32 v77, v77, v81
	s_nop 0
	v_cvt_pk_bf16_f32 v75, v76, v77
	v_exp_f32_e64 v76, -v66
	v_exp_f32_e64 v77, -v67
	v_mul_f32_e32 v66, v66, v70
	v_mul_f32_e32 v67, v67, v71
	v_add_f32_e32 v76, 1.0, v76
	v_add_f32_e32 v77, 1.0, v77
	v_rcp_f32_e32 v76, v76
	v_rcp_f32_e32 v77, v77
	s_nop 0
	v_mul_f32_e32 v66, v76, v66
	v_mul_f32_e32 v67, v77, v67
	s_nop 0
	v_cvt_pk_bf16_f32 v76, v66, v67
	v_exp_f32_e64 v66, -v68
	v_exp_f32_e64 v67, -v69
	v_add_u32_e32 v68, 0x80, v145
	v_add_f32_e32 v66, 1.0, v66
	v_add_f32_e32 v67, 1.0, v67
	v_rcp_f32_e32 v66, v66
	v_rcp_f32_e32 v67, v67
	s_nop 0
	v_mul_f32_e32 v66, v66, v72
	v_mul_f32_e32 v67, v67, v73
	s_nop 0
	v_cvt_pk_bf16_f32 v77, v66, v67
	v_or_b32_e32 v66, 48, v145
	v_mad_i64_i32 v[66:67], s[4:5], v66, s16, v[114:115]
	v_lshl_add_u64 v[66:67], v[66:67], 0, v[116:117]
	global_store_dwordx4 v[66:67], v[74:77], off
	v_exp_f32_e64 v66, -v58
	v_exp_f32_e64 v67, -v59
	v_mul_f32_e32 v58, v58, v62
	v_mul_f32_e32 v59, v59, v63
	v_add_f32_e32 v66, 1.0, v66
	v_add_f32_e32 v67, 1.0, v67
	v_rcp_f32_e32 v66, v66
	v_rcp_f32_e32 v67, v67
	s_nop 0
	v_mul_f32_e32 v58, v66, v58
	v_mul_f32_e32 v59, v67, v59
	s_nop 0
	v_cvt_pk_bf16_f32 v58, v58, v59
	v_exp_f32_e64 v59, -v60
	s_nop 0
	v_add_f32_e32 v59, 1.0, v59
	v_rcp_f32_e32 v60, v59
	v_exp_f32_e64 v59, -v61
	s_nop 0
	v_add_f32_e32 v59, 1.0, v59
	v_rcp_f32_e32 v61, v59
	s_nop 0
	v_mul_f32_e32 v60, v60, v64
	v_mul_f32_e32 v61, v61, v65
	s_nop 0
	v_cvt_pk_bf16_f32 v59, v60, v61
	v_exp_f32_e64 v60, -v50
	v_exp_f32_e64 v61, -v51
	v_mul_f32_e32 v50, v50, v54
	v_mul_f32_e32 v51, v51, v55
	v_add_f32_e32 v60, 1.0, v60
	v_add_f32_e32 v61, 1.0, v61
	v_rcp_f32_e32 v60, v60
	v_rcp_f32_e32 v61, v61
	s_nop 0
	v_mul_f32_e32 v50, v60, v50
	v_mul_f32_e32 v51, v61, v51
	s_nop 0
	v_cvt_pk_bf16_f32 v60, v50, v51
	v_exp_f32_e64 v50, -v52
	v_exp_f32_e64 v51, -v53
	v_add_f32_e32 v50, 1.0, v50
	v_add_f32_e32 v51, 1.0, v51
	v_rcp_f32_e32 v50, v50
	v_rcp_f32_e32 v51, v51
	s_nop 0
	v_mul_f32_e32 v50, v50, v56
	v_mul_f32_e32 v51, v51, v57
	s_nop 0
	v_cvt_pk_bf16_f32 v61, v50, v51
	v_mad_i64_i32 v[50:51], s[4:5], v68, s16, v[114:115]
	v_lshl_add_u64 v[50:51], v[50:51], 0, v[116:117]
	global_store_dwordx4 v[50:51], v[58:61], off
	v_exp_f32_e64 v50, -v42
	v_exp_f32_e64 v51, -v43
	v_mul_f32_e32 v42, v42, v46
	v_mul_f32_e32 v43, v43, v47
	v_add_f32_e32 v50, 1.0, v50
	v_add_f32_e32 v51, 1.0, v51
	v_rcp_f32_e32 v50, v50
	v_rcp_f32_e32 v51, v51
	s_nop 0
	v_mul_f32_e32 v42, v50, v42
	v_mul_f32_e32 v43, v51, v43
	s_nop 0
	v_cvt_pk_bf16_f32 v42, v42, v43
	v_exp_f32_e64 v43, -v44
	s_nop 0
	v_add_f32_e32 v43, 1.0, v43
	v_rcp_f32_e32 v44, v43
	v_exp_f32_e64 v43, -v45
	s_nop 0
	v_add_f32_e32 v43, 1.0, v43
	v_rcp_f32_e32 v45, v43
	s_nop 0
	v_mul_f32_e32 v44, v44, v48
	v_mul_f32_e32 v45, v45, v49
	s_nop 0
	v_cvt_pk_bf16_f32 v43, v44, v45
	v_exp_f32_e64 v44, -v34
	v_exp_f32_e64 v45, -v35
	v_mul_f32_e32 v34, v34, v38
	v_mul_f32_e32 v35, v35, v39
	v_add_f32_e32 v44, 1.0, v44
	v_add_f32_e32 v45, 1.0, v45
	v_rcp_f32_e32 v44, v44
	v_rcp_f32_e32 v45, v45
	s_nop 0
	v_mul_f32_e32 v34, v44, v34
	v_mul_f32_e32 v35, v45, v35
	s_nop 0
	v_cvt_pk_bf16_f32 v44, v34, v35
	v_exp_f32_e64 v34, -v36
	v_exp_f32_e64 v35, -v37
	v_add_f32_e32 v34, 1.0, v34
	v_add_f32_e32 v35, 1.0, v35
	v_rcp_f32_e32 v34, v34
	v_rcp_f32_e32 v35, v35
	s_nop 0
	v_mul_f32_e32 v34, v34, v40
	v_mul_f32_e32 v35, v35, v41
	s_nop 0
	v_cvt_pk_bf16_f32 v45, v34, v35
	v_add_u32_e32 v34, 0x90, v145
	v_mad_i64_i32 v[34:35], s[4:5], v34, s16, v[114:115]
	v_lshl_add_u64 v[34:35], v[34:35], 0, v[116:117]
	global_store_dwordx4 v[34:35], v[42:45], off
	v_exp_f32_e64 v34, -v26
	v_exp_f32_e64 v35, -v27
	v_mul_f32_e32 v26, v26, v30
	v_mul_f32_e32 v27, v27, v31
	v_add_f32_e32 v34, 1.0, v34
	v_add_f32_e32 v35, 1.0, v35
	v_rcp_f32_e32 v34, v34
	v_rcp_f32_e32 v35, v35
	s_nop 0
	v_mul_f32_e32 v26, v34, v26
	v_mul_f32_e32 v27, v35, v27
	s_nop 0
	v_cvt_pk_bf16_f32 v26, v26, v27
	v_exp_f32_e64 v27, -v28
	s_nop 0
	v_add_f32_e32 v27, 1.0, v27
	v_rcp_f32_e32 v28, v27
	v_exp_f32_e64 v27, -v29
	s_nop 0
	v_add_f32_e32 v27, 1.0, v27
	v_rcp_f32_e32 v29, v27
	s_nop 0
	v_mul_f32_e32 v28, v28, v32
	v_mul_f32_e32 v29, v29, v33
	s_nop 0
	v_cvt_pk_bf16_f32 v27, v28, v29
	v_exp_f32_e64 v28, -v18
	v_exp_f32_e64 v29, -v19
	v_mul_f32_e32 v18, v18, v22
	v_mul_f32_e32 v19, v19, v23
	v_add_f32_e32 v28, 1.0, v28
	v_add_f32_e32 v29, 1.0, v29
	v_rcp_f32_e32 v28, v28
	v_rcp_f32_e32 v29, v29
	s_nop 0
	v_mul_f32_e32 v18, v28, v18
	v_mul_f32_e32 v19, v29, v19
	s_nop 0
	v_cvt_pk_bf16_f32 v28, v18, v19
	v_exp_f32_e64 v18, -v20
	v_exp_f32_e64 v19, -v21
	v_add_f32_e32 v18, 1.0, v18
	v_add_f32_e32 v19, 1.0, v19
	v_rcp_f32_e32 v18, v18
	v_rcp_f32_e32 v19, v19
	s_nop 0
	v_mul_f32_e32 v18, v18, v24
	v_mul_f32_e32 v19, v19, v25
	s_nop 0
	v_cvt_pk_bf16_f32 v29, v18, v19
	v_add_u32_e32 v18, 0xa0, v145
	v_mad_i64_i32 v[18:19], s[4:5], v18, s16, v[114:115]
	v_lshl_add_u64 v[18:19], v[18:19], 0, v[116:117]
	global_store_dwordx4 v[18:19], v[26:29], off
	v_exp_f32_e64 v18, -v10
	v_exp_f32_e64 v19, -v11
	v_mul_f32_e32 v10, v10, v14
	v_mul_f32_e32 v11, v11, v15
	v_add_f32_e32 v18, 1.0, v18
	v_add_f32_e32 v19, 1.0, v19
	v_rcp_f32_e32 v18, v18
	v_rcp_f32_e32 v19, v19
	s_nop 0
	v_mul_f32_e32 v10, v18, v10
	v_mul_f32_e32 v11, v19, v11
	s_nop 0
	v_cvt_pk_bf16_f32 v10, v10, v11
	v_exp_f32_e64 v11, -v12
	s_nop 0
	v_add_f32_e32 v11, 1.0, v11
	v_rcp_f32_e32 v12, v11
	v_exp_f32_e64 v11, -v13
	s_nop 0
	v_add_f32_e32 v11, 1.0, v11
	v_rcp_f32_e32 v13, v11
	s_nop 0
	v_mul_f32_e32 v12, v12, v16
	v_mul_f32_e32 v13, v13, v17
	s_nop 0
	v_cvt_pk_bf16_f32 v11, v12, v13
	v_exp_f32_e64 v12, -v2
	v_exp_f32_e64 v13, -v3
	v_mul_f32_e32 v2, v2, v6
	v_mul_f32_e32 v3, v3, v7
	v_add_f32_e32 v12, 1.0, v12
	v_add_f32_e32 v13, 1.0, v13
	v_rcp_f32_e32 v12, v12
	v_rcp_f32_e32 v13, v13
	s_nop 0
	v_mul_f32_e32 v2, v12, v2
	v_mul_f32_e32 v3, v13, v3
	s_nop 0
	v_cvt_pk_bf16_f32 v12, v2, v3
	v_exp_f32_e64 v2, -v4
	v_exp_f32_e64 v3, -v5
	v_add_f32_e32 v2, 1.0, v2
	v_add_f32_e32 v3, 1.0, v3
	v_rcp_f32_e32 v2, v2
	v_rcp_f32_e32 v3, v3
	s_nop 0
	v_mul_f32_e32 v2, v2, v8
	v_mul_f32_e32 v3, v3, v9
	s_nop 0
	v_cvt_pk_bf16_f32 v13, v2, v3
	v_add_u32_e32 v2, 0xb0, v145
	v_mad_i64_i32 v[2:3], s[4:5], v2, s16, v[114:115]
	v_lshl_add_u64 v[2:3], v[2:3], 0, v[116:117]
	s_mov_b64 s[4:5], -1
	global_store_dwordx4 v[2:3], v[10:13], off
	s_cbranch_vccnz .LBB0_1660
	s_andn2_b64 vcc, exec, s[36:37]
	s_cbranch_vccnz .LBB0_1659
	s_barrier
	s_branch .LBB0_1659
